# P8 wide row pass: bf16 a2 stores non-temporal
# speedup vs baseline: 1.0049x; 1.0049x over previous
; __device__ __forceinline__ float wave_sum(float v) { for (int o = 32; o >= 1; o >>= 1) v += __shfl_xor(v, o); return v; }
; __device__ __forceinline__ u32x2 pk4(f32x4 v) { u32x2 w; w.x = cvt_pk_bf16(v[0], v[1]); w.y = cvt_pk_bf16(v[2], v[3]); return w; }
; __device__ __forceinline__ f32x4 up4(u32x2 w) { return (f32x4){bf_lo(w.x), bf_hi(w.x), bf_lo(w.y), bf_hi(w.y)}; }
; __device__ __forceinline__ void row_pass1(const Args& a, int row_lo, int row_hi, int gw, int NGW, int lane) {
;     ...
;     for (int r0 = row_lo + 2 * gw; r0 < row_hi; r0 += 2 * NGW) {
;         f32x4 xv[2][4]; u32x2 yv[2][4]; float rs[2];
; #pragma unroll
;         for (int r = 0; r < 2; ++r) { const int row = (r0 + r < row_hi) ? r0 + r : r0; rs[r] = rss[row];
;             const f32x4* xr = (const f32x4*)xrow_ptr(a, row) + lane; const u32x2* yr = (const u32x2*)(Y + (size_t)row * DM) + lane;
; #pragma unroll
;             for (int j = 0; j < 4; ++j) { xv[r][j] = xr[64 * j]; yv[r][j] = yr[64 * j]; } }
; #pragma unroll
;         for (int r = 0; r < 2; ++r) { const int row = r0 + r; if (row >= row_hi) break;
;             const float rstd = rsqrtf(rs[r] * (1.f / DM) + EPS); f32x4 v[4]; float s = 0.f;
; #pragma unroll
;             for (int j = 0; j < 4; ++j) { v[j] = xv[r][j] + up4(yv[r][j]) * rstd * gp[j]; s += (v[j][0] * v[j][0] + v[j][1] * v[j][1]) + (v[j][2] * v[j][2] + v[j][3] * v[j][3]); }
;             const float rstd2 = rsqrtf(wave_sum(s) * (1.f / DM) + EPS);
;             f32x4* xo = (f32x4*)(XO + (size_t)row * DM) + lane; u32x2* ao = (u32x2*)(A2 + (size_t)row * DM) + lane;
; #pragma unroll
;             for (int j = 0; j < 4; ++j) { xo[64 * j] = v[j]; ao[64 * j] = pk4(v[j] * rstd2 * gq[j]); } }
.Lx8_loop:
	global_load_dwordx2 v[80:81], v197, s[16:17]
	global_load_dwordx4 v[48:51], v198, s[24:25] nt
	global_load_dwordx4 v[52:55], v198, s[24:25] offset:1024 nt
	global_load_dwordx4 v[16:19], v148, s[20:21] nt
	global_load_dwordx4 v[20:23], v148, s[20:21] offset:16 nt
	global_load_dwordx4 v[24:27], v148, s[20:21] offset:2048 nt
	global_load_dwordx4 v[28:31], v148, s[20:21] offset:2064 nt
	global_load_dwordx4 v[56:59], v198, s[24:25] offset:2048 nt
	global_load_dwordx4 v[60:63], v198, s[24:25] offset:3072 nt
	global_load_dwordx4 v[32:35], v149, s[20:21] nt
	global_load_dwordx4 v[36:39], v149, s[20:21] offset:16 nt
	global_load_dwordx4 v[40:43], v149, s[20:21] offset:2048 nt
	global_load_dwordx4 v[44:47], v149, s[20:21] offset:2064 nt
	s_waitcnt vmcnt(6)
	v_fmamk_f32 v104, v80, 0x3a800000, v116
	v_mul_f32_e32 v105, 0x4b800000, v104
	v_cmp_gt_f32_e32 vcc, s101, v104
	s_nop 1
	v_cndmask_b32_e32 v104, v104, v105, vcc
	v_rsq_f32_e32 v104, v104
	s_nop 0
	v_mul_f32_e32 v105, 0x45800000, v104
	v_cndmask_b32_e32 v104, v104, v105, vcc
	v_lshlrev_b32_e32 v120, 16, v48
	v_and_b32_e32 v121, 0xffff0000, v48
	v_lshlrev_b32_e32 v122, 16, v49
	v_and_b32_e32 v123, 0xffff0000, v49
	v_pk_mul_f32 v[120:121], v[104:105], v[120:121] op_sel_hi:[0,1]
	v_pk_mul_f32 v[122:123], v[104:105], v[122:123] op_sel_hi:[0,1]
	v_pk_fma_f32 v[16:17], v[84:85], v[120:121], v[16:17]
	v_pk_fma_f32 v[18:19], v[86:87], v[122:123], v[18:19]
	v_lshlrev_b32_e32 v124, 16, v50
	v_and_b32_e32 v125, 0xffff0000, v50
	v_lshlrev_b32_e32 v126, 16, v51
	v_and_b32_e32 v127, 0xffff0000, v51
	v_pk_mul_f32 v[124:125], v[104:105], v[124:125] op_sel_hi:[0,1]
	v_pk_mul_f32 v[126:127], v[104:105], v[126:127] op_sel_hi:[0,1]
	v_pk_fma_f32 v[20:21], v[88:89], v[124:125], v[20:21]
	v_pk_fma_f32 v[22:23], v[90:91], v[126:127], v[22:23]
	v_lshlrev_b32_e32 v128, 16, v52
	v_and_b32_e32 v129, 0xffff0000, v52
	v_lshlrev_b32_e32 v130, 16, v53
	v_and_b32_e32 v131, 0xffff0000, v53
	v_pk_mul_f32 v[128:129], v[104:105], v[128:129] op_sel_hi:[0,1]
	v_pk_mul_f32 v[130:131], v[104:105], v[130:131] op_sel_hi:[0,1]
	v_pk_fma_f32 v[24:25], v[92:93], v[128:129], v[24:25]
	v_pk_fma_f32 v[26:27], v[94:95], v[130:131], v[26:27]
	v_lshlrev_b32_e32 v132, 16, v54
	v_and_b32_e32 v133, 0xffff0000, v54
	v_lshlrev_b32_e32 v134, 16, v55
	v_and_b32_e32 v135, 0xffff0000, v55
	v_pk_mul_f32 v[132:133], v[104:105], v[132:133] op_sel_hi:[0,1]
	v_pk_mul_f32 v[134:135], v[104:105], v[134:135] op_sel_hi:[0,1]
	v_pk_fma_f32 v[28:29], v[96:97], v[132:133], v[28:29]
	v_pk_fma_f32 v[30:31], v[98:99], v[134:135], v[30:31]
	v_pk_mul_f32 v[200:201], v[16:17], v[16:17]
	v_pk_fma_f32 v[200:201], v[18:19], v[18:19], v[200:201]
	v_pk_mul_f32 v[202:203], v[20:21], v[20:21]
	v_pk_fma_f32 v[202:203], v[22:23], v[22:23], v[202:203]
	v_pk_add_f32 v[200:201], v[200:201], v[202:203]
	v_pk_mul_f32 v[202:203], v[24:25], v[24:25]
	v_pk_fma_f32 v[202:203], v[26:27], v[26:27], v[202:203]
	v_pk_add_f32 v[200:201], v[200:201], v[202:203]
	v_pk_mul_f32 v[202:203], v[28:29], v[28:29]
	v_pk_fma_f32 v[202:203], v[30:31], v[30:31], v[202:203]
	v_pk_add_f32 v[200:201], v[200:201], v[202:203]
	v_add_f32_e32 v200, v200, v201
	s_nop 1
	v_add_f32_dpp v200, v200, v200 quad_perm:[1,0,3,2] row_mask:0xf bank_mask:0xf
	s_nop 1
	v_add_f32_dpp v200, v200, v200 quad_perm:[2,3,0,1] row_mask:0xf bank_mask:0xf
	s_nop 1
	v_add_f32_dpp v200, v200, v200 row_half_mirror row_mask:0xf bank_mask:0xf
	s_nop 1
	v_add_f32_dpp v200, v200, v200 row_mirror row_mask:0xf bank_mask:0xf
	v_mov_b32_e32 v201, v200
	s_nop 1
	v_permlane16_swap_b32_e32 v200, v201
	v_add_f32_e32 v200, v200, v201
	v_mov_b32_e32 v201, v200
	s_nop 1
	v_permlane32_swap_b32_e32 v200, v201
	v_add_f32_e32 v200, v200, v201
	v_fmamk_f32 v106, v200, 0x3a800000, v116
	v_mul_f32_e32 v107, 0x4b800000, v106
	v_cmp_gt_f32_e32 vcc, s101, v106
	s_nop 1
	v_cndmask_b32_e32 v106, v106, v107, vcc
	v_rsq_f32_e32 v106, v106
	s_nop 0
	v_mul_f32_e32 v107, 0x45800000, v106
	v_cndmask_b32_e32 v106, v106, v107, vcc
	v_pk_mul_f32 v[204:205], v[16:17], v[106:107] op_sel_hi:[1,0]
	v_pk_mul_f32 v[206:207], v[18:19], v[106:107] op_sel_hi:[1,0]
	v_pk_mul_f32 v[204:205], v[180:181], v[204:205]
	v_pk_mul_f32 v[206:207], v[182:183], v[206:207]
	v_pk_mul_f32 v[208:209], v[20:21], v[106:107] op_sel_hi:[1,0]
	v_pk_mul_f32 v[210:211], v[22:23], v[106:107] op_sel_hi:[1,0]
	v_pk_mul_f32 v[208:209], v[184:185], v[208:209]
	v_pk_mul_f32 v[210:211], v[186:187], v[210:211]
	v_pk_mul_f32 v[212:213], v[24:25], v[106:107] op_sel_hi:[1,0]
	v_pk_mul_f32 v[214:215], v[26:27], v[106:107] op_sel_hi:[1,0]
	v_pk_mul_f32 v[212:213], v[188:189], v[212:213]
	v_pk_mul_f32 v[214:215], v[190:191], v[214:215]
	v_pk_mul_f32 v[216:217], v[28:29], v[106:107] op_sel_hi:[1,0]
	v_pk_mul_f32 v[218:219], v[30:31], v[106:107] op_sel_hi:[1,0]
	v_pk_mul_f32 v[216:217], v[192:193], v[216:217]
	v_pk_mul_f32 v[218:219], v[194:195], v[218:219]
	v_cvt_pk_bf16_f32 v220, v204, v205
	v_cvt_pk_bf16_f32 v221, v206, v207
	v_cvt_pk_bf16_f32 v222, v208, v209
	v_cvt_pk_bf16_f32 v223, v210, v211
	v_cvt_pk_bf16_f32 v224, v212, v213
	v_cvt_pk_bf16_f32 v225, v214, v215
	v_cvt_pk_bf16_f32 v226, v216, v217
	v_cvt_pk_bf16_f32 v227, v218, v219
	global_store_dwordx4 v198, v[220:223], s[26:27] nt
	global_store_dwordx4 v198, v[224:227], s[26:27] offset:1024 nt
	s_waitcnt vmcnt(2)
; __device__ __forceinline__ float wave_sum(float v) { for (int o = 32; o >= 1; o >>= 1) v += __shfl_xor(v, o); return v; }
; __device__ __forceinline__ u32x2 pk4(f32x4 v) { u32x2 w; w.x = cvt_pk_bf16(v[0], v[1]); w.y = cvt_pk_bf16(v[2], v[3]); return w; }
; __device__ __forceinline__ f32x4 up4(u32x2 w) { return (f32x4){bf_lo(w.x), bf_hi(w.x), bf_lo(w.y), bf_hi(w.y)}; }
; __device__ __forceinline__ void row_pass1(const Args& a, int row_lo, int row_hi, int gw, int NGW, int lane) {
;     ...
;     for (int r0 = row_lo + 2 * gw; r0 < row_hi; r0 += 2 * NGW) {
;         f32x4 xv[2][4]; u32x2 yv[2][4]; float rs[2];
; #pragma unroll
;         for (int r = 0; r < 2; ++r) { const int row = (r0 + r < row_hi) ? r0 + r : r0; rs[r] = rss[row];
;             const f32x4* xr = (const f32x4*)xrow_ptr(a, row) + lane; const u32x2* yr = (const u32x2*)(Y + (size_t)row * DM) + lane;
; #pragma unroll
;             for (int j = 0; j < 4; ++j) { xv[r][j] = xr[64 * j]; yv[r][j] = yr[64 * j]; } }
; #pragma unroll
;         for (int r = 0; r < 2; ++r) { const int row = r0 + r; if (row >= row_hi) break;
;             const float rstd = rsqrtf(rs[r] * (1.f / DM) + EPS); f32x4 v[4]; float s = 0.f;
; #pragma unroll
;             for (int j = 0; j < 4; ++j) { v[j] = xv[r][j] + up4(yv[r][j]) * rstd * gp[j]; s += (v[j][0] * v[j][0] + v[j][1] * v[j][1]) + (v[j][2] * v[j][2] + v[j][3] * v[j][3]); }
;             const float rstd2 = rsqrtf(wave_sum(s) * (1.f / DM) + EPS);
;             f32x4* xo = (f32x4*)(XO + (size_t)row * DM) + lane; u32x2* ao = (u32x2*)(A2 + (size_t)row * DM) + lane;
; #pragma unroll
;             for (int j = 0; j < 4; ++j) { xo[64 * j] = v[j]; ao[64 * j] = pk4(v[j] * rstd2 * gq[j]); } }
	v_fmamk_f32 v104, v81, 0x3a800000, v116
	v_mul_f32_e32 v105, 0x4b800000, v104
	v_cmp_gt_f32_e32 vcc, s101, v104
	s_nop 1
	v_cndmask_b32_e32 v104, v104, v105, vcc
	v_rsq_f32_e32 v104, v104
	s_nop 0
	v_mul_f32_e32 v105, 0x45800000, v104
	v_cndmask_b32_e32 v104, v104, v105, vcc
	v_lshlrev_b32_e32 v120, 16, v56
	v_and_b32_e32 v121, 0xffff0000, v56
	v_lshlrev_b32_e32 v122, 16, v57
	v_and_b32_e32 v123, 0xffff0000, v57
	v_pk_mul_f32 v[120:121], v[104:105], v[120:121] op_sel_hi:[0,1]
	v_pk_mul_f32 v[122:123], v[104:105], v[122:123] op_sel_hi:[0,1]
	v_pk_fma_f32 v[32:33], v[84:85], v[120:121], v[32:33]
	v_pk_fma_f32 v[34:35], v[86:87], v[122:123], v[34:35]
	v_lshlrev_b32_e32 v124, 16, v58
	v_and_b32_e32 v125, 0xffff0000, v58
	v_lshlrev_b32_e32 v126, 16, v59
	v_and_b32_e32 v127, 0xffff0000, v59
	v_pk_mul_f32 v[124:125], v[104:105], v[124:125] op_sel_hi:[0,1]
	v_pk_mul_f32 v[126:127], v[104:105], v[126:127] op_sel_hi:[0,1]
	v_pk_fma_f32 v[36:37], v[88:89], v[124:125], v[36:37]
	v_pk_fma_f32 v[38:39], v[90:91], v[126:127], v[38:39]
	v_lshlrev_b32_e32 v128, 16, v60
	v_and_b32_e32 v129, 0xffff0000, v60
	v_lshlrev_b32_e32 v130, 16, v61
	v_and_b32_e32 v131, 0xffff0000, v61
	v_pk_mul_f32 v[128:129], v[104:105], v[128:129] op_sel_hi:[0,1]
	v_pk_mul_f32 v[130:131], v[104:105], v[130:131] op_sel_hi:[0,1]
	v_pk_fma_f32 v[40:41], v[92:93], v[128:129], v[40:41]
	v_pk_fma_f32 v[42:43], v[94:95], v[130:131], v[42:43]
	v_lshlrev_b32_e32 v132, 16, v62
	v_and_b32_e32 v133, 0xffff0000, v62
	v_lshlrev_b32_e32 v134, 16, v63
	v_and_b32_e32 v135, 0xffff0000, v63
	v_pk_mul_f32 v[132:133], v[104:105], v[132:133] op_sel_hi:[0,1]
	v_pk_mul_f32 v[134:135], v[104:105], v[134:135] op_sel_hi:[0,1]
	v_pk_fma_f32 v[44:45], v[96:97], v[132:133], v[44:45]
	v_pk_fma_f32 v[46:47], v[98:99], v[134:135], v[46:47]
	v_pk_mul_f32 v[200:201], v[32:33], v[32:33]
	v_pk_fma_f32 v[200:201], v[34:35], v[34:35], v[200:201]
	v_pk_mul_f32 v[202:203], v[36:37], v[36:37]
	v_pk_fma_f32 v[202:203], v[38:39], v[38:39], v[202:203]
	v_pk_add_f32 v[200:201], v[200:201], v[202:203]
	v_pk_mul_f32 v[202:203], v[40:41], v[40:41]
	v_pk_fma_f32 v[202:203], v[42:43], v[42:43], v[202:203]
	v_pk_add_f32 v[200:201], v[200:201], v[202:203]
	v_pk_mul_f32 v[202:203], v[44:45], v[44:45]
	v_pk_fma_f32 v[202:203], v[46:47], v[46:47], v[202:203]
	v_pk_add_f32 v[200:201], v[200:201], v[202:203]
	v_add_f32_e32 v200, v200, v201
	s_nop 1
	v_add_f32_dpp v200, v200, v200 quad_perm:[1,0,3,2] row_mask:0xf bank_mask:0xf
	s_nop 1
	v_add_f32_dpp v200, v200, v200 quad_perm:[2,3,0,1] row_mask:0xf bank_mask:0xf
	s_nop 1
	v_add_f32_dpp v200, v200, v200 row_half_mirror row_mask:0xf bank_mask:0xf
	s_nop 1
	v_add_f32_dpp v200, v200, v200 row_mirror row_mask:0xf bank_mask:0xf
	v_mov_b32_e32 v201, v200
	s_nop 1
	v_permlane16_swap_b32_e32 v200, v201
	v_add_f32_e32 v200, v200, v201
	v_mov_b32_e32 v201, v200
	s_nop 1
	v_permlane32_swap_b32_e32 v200, v201
	v_add_f32_e32 v200, v200, v201
	v_fmamk_f32 v106, v200, 0x3a800000, v116
	v_mul_f32_e32 v107, 0x4b800000, v106
	v_cmp_gt_f32_e32 vcc, s101, v106
	s_nop 1
	v_cndmask_b32_e32 v106, v106, v107, vcc
	v_rsq_f32_e32 v106, v106
	s_nop 0
	v_mul_f32_e32 v107, 0x45800000, v106
	v_cndmask_b32_e32 v106, v106, v107, vcc
	v_pk_mul_f32 v[204:205], v[32:33], v[106:107] op_sel_hi:[1,0]
	v_pk_mul_f32 v[206:207], v[34:35], v[106:107] op_sel_hi:[1,0]
	v_pk_mul_f32 v[204:205], v[180:181], v[204:205]
	v_pk_mul_f32 v[206:207], v[182:183], v[206:207]
	v_pk_mul_f32 v[208:209], v[36:37], v[106:107] op_sel_hi:[1,0]
	v_pk_mul_f32 v[210:211], v[38:39], v[106:107] op_sel_hi:[1,0]
	v_pk_mul_f32 v[208:209], v[184:185], v[208:209]
	v_pk_mul_f32 v[210:211], v[186:187], v[210:211]
	v_pk_mul_f32 v[212:213], v[40:41], v[106:107] op_sel_hi:[1,0]
	v_pk_mul_f32 v[214:215], v[42:43], v[106:107] op_sel_hi:[1,0]
	v_pk_mul_f32 v[212:213], v[188:189], v[212:213]
	v_pk_mul_f32 v[214:215], v[190:191], v[214:215]
	v_pk_mul_f32 v[216:217], v[44:45], v[106:107] op_sel_hi:[1,0]
	v_pk_mul_f32 v[218:219], v[46:47], v[106:107] op_sel_hi:[1,0]
	v_pk_mul_f32 v[216:217], v[192:193], v[216:217]
	v_pk_mul_f32 v[218:219], v[194:195], v[218:219]
	v_cvt_pk_bf16_f32 v220, v204, v205
	v_cvt_pk_bf16_f32 v221, v206, v207
	v_cvt_pk_bf16_f32 v222, v208, v209
	v_cvt_pk_bf16_f32 v223, v210, v211
	v_cvt_pk_bf16_f32 v224, v212, v213
	v_cvt_pk_bf16_f32 v225, v214, v215
	v_cvt_pk_bf16_f32 v226, v216, v217
	v_cvt_pk_bf16_f32 v227, v218, v219
	global_store_dwordx4 v198, v[220:223], s[26:27] offset:2048 nt
	global_store_dwordx4 v198, v[224:227], s[26:27] offset:3072 nt
	s_add_i32 s0, s0, s10
	s_add_u32 s20, s20, s98
	s_addc_u32 s21, s21, 0
	s_add_u32 s24, s24, s99
	s_addc_u32 s25, s25, 0
	s_add_u32 s26, s26, s99
	s_addc_u32 s27, s27, 0
	s_add_u32 s16, s16, s100
	s_addc_u32 s17, s17, 0
	s_cmpk_gt_i32 s0, 0x3fff
	s_cbranch_scc0 .Lx8_loop
